# P3 out-proj RECON epilogue: all residual/xinv loads of the 8 row groups prefetched up front into dead fragment VGPRs (v_mov at use), per-group vmcnt waits no longer wait on previous group's stores
# baseline (speedup 1.0000x reference)
; __device__ __forceinline__ unsigned cvt_pk_bf16(float lo, float hi) { unsigned r; asm volatile("v_cvt_pk_bf16_f32 %0, %1, %2" : "=v"(r) : "v"(lo), "v"(hi)); return r; }
;     __device__ __forceinline__ void operator()(const f32x4 (&acc)[2][2][4][2], const Unit& u, int wr, int wc, int fr, int fq) const {
;     ...
;         f32x4 gi[2][2];
;         if constexpr (RECON) {
; #pragma unroll
;             for (int bj = 0; bj < 2; ++bj)
; #pragma unroll
;                 for (int n = 0; n < 2; ++n) { const f32x4 g = *(const f32x4*)(g1 + col0 + bj * HALF + n * 4); gi[bj][n] = (f32x4){__builtin_amdgcn_rcpf(g[0]), __builtin_amdgcn_rcpf(g[1]), __builtin_amdgcn_rcpf(g[2]), __builtin_amdgcn_rcpf(g[3])}; }
;         }
; #pragma unroll
;         for (int ai = 0; ai < 2; ++ai)
; #pragma unroll
;             for (int m = 0; m < 4; ++m) { const int r = rowt + ai * HALF + wr * 64 + m * 16 + fr; const size_t off = (size_t)r * 1024 + col0; float ss = 0.f;
;                 float xi = 0.f; if constexpr (RECON) xi = xinv[r];
; #pragma unroll
;                 for (int bj = 0; bj < 2; ++bj) { f32x4 b0, b1;
;                     if constexpr (RECON) { const u32x4 w = *(const u32x4*)(xb + off + bj * HALF);
;                         b0 = (f32x4){__builtin_bit_cast(float, w.x << 16), __builtin_bit_cast(float, w.x & 0xffff0000u), __builtin_bit_cast(float, w.y << 16), __builtin_bit_cast(float, w.y & 0xffff0000u)} * xi * gi[bj][0];
;                         b1 = (f32x4){__builtin_bit_cast(float, w.z << 16), __builtin_bit_cast(float, w.z & 0xffff0000u), __builtin_bit_cast(float, w.w << 16), __builtin_bit_cast(float, w.w & 0xffff0000u)} * xi * gi[bj][1]; }
;                     else { b0 = *(const f32x4*)(base + off + bj * HALF); b1 = *(const f32x4*)(base + off + bj * HALF + 4); }
;                     const f32x4 o0 = b0 + acc[ai][bj][m][0], o1 = b1 + acc[ai][bj][m][1];
;                     ss += ((o0[0] * o0[0] + o0[1] * o0[1]) + (o0[2] * o0[2] + o0[3] * o0[3])) + ((o1[0] * o1[0] + o1[1] * o1[1]) + (o1[2] * o1[2] + o1[3] * o1[3]));
;                     u32x4 w2; w2.x = cvt_pk_bf16(o0[0], o0[1]); w2.y = cvt_pk_bf16(o0[2], o0[3]); w2.z = cvt_pk_bf16(o1[0], o1[1]); w2.w = cvt_pk_bf16(o1[2], o1[3]); *(u32x4*)(xb + off + bj * HALF) = w2; }
;                 ss += __shfl_xor(ss, 16); ss += __shfl_xor(ss, 32);
;                 if (fq == 0) stats[(size_t)r * 16 + u.pn * 4 + wc] = ss;
.LBB0_1233:
	v_lshl_or_b32 v144, s16, 8, v165
	v_lshl_add_u32 v154, s28, 8, v164
	v_ashrrev_i32_e32 v145, 31, v144
	v_ashrrev_i32_e32 v155, 31, v154
	v_lshl_add_u64 v[146:147], v[144:145], 2, s[48:49]
	v_lshlrev_b64 v[152:153], 11, v[154:155]
	global_load_dwordx4 v[148:151], v[146:147], off
	global_load_dwordx4 v[172:175], v[146:147], off offset:16
	v_lshl_add_u64 v[152:153], s[66:67], 0, v[152:153]
	v_lshl_add_u64 v[192:193], v[144:145], 1, v[152:153]
	global_load_dwordx4 v[176:179], v[192:193], off
	v_lshl_add_u64 v[152:153], v[154:155], 2, s[80:81]
	global_load_dword v194, v[152:153], off
	global_load_dwordx4 v[180:183], v[146:147], off offset:528
	global_load_dwordx4 v[184:187], v[146:147], off offset:512
	global_load_dwordx4 v[188:191], v[192:193], off offset:256
	v_add_u32_e32 v203, 0x10, v154
	v_lshlrev_b32_e32 v204, 2, v203
	v_lshlrev_b32_e32 v203, 11, v203
	v_lshl_add_u32 v203, v144, 1, v203
	global_load_dwordx4 v[210:213], v203, s[66:67]
	global_load_dword v250, v204, s[80:81]
	global_load_dwordx4 v[214:217], v203, s[66:67] offset:256
	v_add_u32_e32 v203, 0x20, v154
	v_lshlrev_b32_e32 v204, 2, v203
	v_lshlrev_b32_e32 v203, 11, v203
	v_lshl_add_u32 v203, v144, 1, v203
	global_load_dwordx4 v[218:221], v203, s[66:67]
	global_load_dword v251, v204, s[80:81]
	global_load_dwordx4 v[222:225], v203, s[66:67] offset:256
	v_add_u32_e32 v203, 0x30, v154
	v_lshlrev_b32_e32 v204, 2, v203
	v_lshlrev_b32_e32 v203, 11, v203
	v_lshl_add_u32 v203, v144, 1, v203
	global_load_dwordx4 v[226:229], v203, s[66:67]
	global_load_dword v252, v204, s[80:81]
	global_load_dwordx4 v[230:233], v203, s[66:67] offset:256
	v_add_u32_e32 v203, 0x80, v154
	v_lshlrev_b32_e32 v204, 2, v203
	v_lshlrev_b32_e32 v203, 11, v203
	v_lshl_add_u32 v203, v144, 1, v203
	global_load_dwordx4 v[234:237], v203, s[66:67]
	global_load_dword v253, v204, s[80:81]
	global_load_dwordx4 v[238:241], v203, s[66:67] offset:256
	v_add_u32_e32 v203, 0x90, v154
	v_lshlrev_b32_e32 v204, 2, v203
	v_lshlrev_b32_e32 v203, 11, v203
	v_lshl_add_u32 v203, v144, 1, v203
	global_load_dwordx4 v[242:245], v203, s[66:67]
	global_load_dword v202, v204, s[80:81]
	global_load_dwordx4 v[246:249], v203, s[66:67] offset:256
	s_lshl_b32 s28, s16, 2
	s_ashr_i32 s29, s28, 31
	s_waitcnt vmcnt(15)
	v_rcp_f32_e32 v148, v148
	v_rcp_f32_e32 v149, v149
	v_rcp_f32_e32 v152, v150
	v_rcp_f32_e32 v153, v151
	v_rcp_f32_e32 v146, v172
	v_rcp_f32_e32 v147, v173
	v_rcp_f32_e32 v150, v174
	v_rcp_f32_e32 v151, v175
	v_lshlrev_b32_e32 v172, 16, v176
	v_and_b32_e32 v173, 0xffff0000, v176
	v_lshlrev_b32_e32 v174, 16, v177
	v_and_b32_e32 v175, 0xffff0000, v177
	v_lshlrev_b32_e32 v176, 16, v178
	v_and_b32_e32 v177, 0xffff0000, v178
	v_lshlrev_b32_e32 v178, 16, v179
	v_and_b32_e32 v179, 0xffff0000, v179
	v_pk_mul_f32 v[172:173], v[194:195], v[172:173] op_sel_hi:[0,1]
	v_pk_mul_f32 v[174:175], v[194:195], v[174:175] op_sel_hi:[0,1]
	v_pk_mul_f32 v[176:177], v[194:195], v[176:177] op_sel_hi:[0,1]
	v_pk_mul_f32 v[178:179], v[194:195], v[178:179] op_sel_hi:[0,1]
	v_pk_fma_f32 v[196:197], v[152:153], v[174:175], v[128:129]
	v_pk_fma_f32 v[198:199], v[148:149], v[172:173], v[126:127]
	v_pk_fma_f32 v[178:179], v[150:151], v[178:179], v[124:125]
	v_pk_fma_f32 v[200:201], v[146:147], v[176:177], v[122:123]
	v_cvt_pk_bf16_f32 v174, v198, v199
	v_cvt_pk_bf16_f32 v175, v196, v197
	v_and_b32_e32 v123, 64, v169
	v_cvt_pk_bf16_f32 v176, v200, v201
	v_cvt_pk_bf16_f32 v177, v178, v179
	v_xor_b32_e32 v122, 16, v169
	v_add_u32_e32 v195, 64, v123
	v_cmp_lt_i32_e32 vcc, v122, v195
	v_rcp_f32_e32 v123, v181
	v_rcp_f32_e32 v126, v182
	v_cndmask_b32_e32 v122, v169, v122, vcc
	v_lshlrev_b32_e32 v172, 2, v122
	v_rcp_f32_e32 v122, v180
	v_mul_f32_e32 v180, v199, v199
	v_mul_f32_e32 v181, v197, v197
	v_mul_f32_e32 v182, v201, v201
	v_mul_f32_e32 v179, v179, v179
	v_rcp_f32_e32 v124, v184
	v_rcp_f32_e32 v125, v185
	v_rcp_f32_e32 v128, v186
	v_rcp_f32_e32 v129, v187
	v_rcp_f32_e32 v127, v183
	v_fmac_f32_e32 v180, v198, v198
	v_fmac_f32_e32 v181, v196, v196
	v_fmac_f32_e32 v182, v200, v200
	v_fmac_f32_e32 v179, v178, v178
	v_add_f32_e32 v178, v180, v181
	v_add_f32_e32 v179, v182, v179
	v_add_f32_e32 v186, v178, v179
	v_xor_b32_e32 v173, 32, v169
	v_cmp_lt_i32_e32 vcc, v173, v195
	global_store_dwordx4 v[192:193], v[174:177], off
	v_lshlrev_b32_e32 v178, 16, v188
	v_and_b32_e32 v179, 0xffff0000, v188
	v_lshlrev_b32_e32 v180, 16, v189
	v_and_b32_e32 v181, 0xffff0000, v189
	v_lshlrev_b32_e32 v182, 16, v190
	v_and_b32_e32 v183, 0xffff0000, v190
	v_lshlrev_b32_e32 v184, 16, v191
	v_and_b32_e32 v185, 0xffff0000, v191
	v_pk_mul_f32 v[178:179], v[194:195], v[178:179] op_sel_hi:[0,1]
	v_pk_mul_f32 v[180:181], v[194:195], v[180:181] op_sel_hi:[0,1]
	v_pk_mul_f32 v[182:183], v[194:195], v[182:183] op_sel_hi:[0,1]
	v_pk_mul_f32 v[184:185], v[194:195], v[184:185] op_sel_hi:[0,1]
	v_pk_fma_f32 v[120:121], v[128:129], v[180:181], v[120:121]
	v_pk_fma_f32 v[118:119], v[124:125], v[178:179], v[118:119]
	v_pk_fma_f32 v[178:179], v[126:127], v[184:185], v[116:117]
	v_pk_fma_f32 v[180:181], v[122:123], v[182:183], v[114:115]
	v_mul_f32_e32 v114, v119, v119
	v_mul_f32_e32 v115, v121, v121
	v_mul_f32_e32 v116, v181, v181
	v_mul_f32_e32 v117, v179, v179
	v_fmac_f32_e32 v114, v118, v118
	v_fmac_f32_e32 v115, v120, v120
	v_fmac_f32_e32 v116, v180, v180
	v_fmac_f32_e32 v117, v178, v178
	v_add_f32_e32 v114, v114, v115
	v_add_f32_e32 v115, v116, v117
	v_add_f32_e32 v114, v114, v115
	v_add_f32_e32 v114, v186, v114
	ds_bpermute_b32 v115, v172, v114
	v_cndmask_b32_e32 v116, v169, v173, vcc
	v_lshlrev_b32_e32 v116, 2, v116
	v_cvt_pk_bf16_f32 v118, v118, v119
	v_cvt_pk_bf16_f32 v119, v120, v121
	s_waitcnt lgkmcnt(0)
	v_add_f32_e32 v114, v114, v115
	ds_bpermute_b32 v115, v116, v114
	v_cvt_pk_bf16_f32 v120, v180, v181
	v_cvt_pk_bf16_f32 v121, v178, v179
	global_store_dwordx4 v[192:193], v[118:121], off offset:256
	s_and_saveexec_b64 s[30:31], s[6:7]
	s_cbranch_execz .LBB0_1235
	v_lshlrev_b64 v[118:119], 6, v[154:155]
	v_lshl_add_u64 v[118:119], s[8:9], 0, v[118:119]
	v_lshl_add_u64 v[118:119], s[28:29], 2, v[118:119]
	s_lshl_b32 s16, s53, 2
	v_lshl_add_u64 v[118:119], v[118:119], 0, s[16:17]
	s_waitcnt lgkmcnt(0)
	v_add_f32_e32 v114, v114, v115
	global_store_dword v[118:119], v114, off
; __device__ __forceinline__ unsigned cvt_pk_bf16(float lo, float hi) { unsigned r; asm volatile("v_cvt_pk_bf16_f32 %0, %1, %2" : "=v"(r) : "v"(lo), "v"(hi)); return r; }
;     __device__ __forceinline__ void operator()(const f32x4 (&acc)[2][2][4][2], const Unit& u, int wr, int wc, int fr, int fq) const {
;     ...
;         for (int ai = 0; ai < 2; ++ai)
; #pragma unroll
;             for (int m = 0; m < 4; ++m) { const int r = rowt + ai * HALF + wr * 64 + m * 16 + fr; const size_t off = (size_t)r * 1024 + col0; float ss = 0.f;
;                 float xi = 0.f; if constexpr (RECON) xi = xinv[r];
; #pragma unroll
;                 for (int bj = 0; bj < 2; ++bj) { f32x4 b0, b1;
;                     if constexpr (RECON) { const u32x4 w = *(const u32x4*)(xb + off + bj * HALF);
;                         b0 = (f32x4){__builtin_bit_cast(float, w.x << 16), __builtin_bit_cast(float, w.x & 0xffff0000u), __builtin_bit_cast(float, w.y << 16), __builtin_bit_cast(float, w.y & 0xffff0000u)} * xi * gi[bj][0];
;                         b1 = (f32x4){__builtin_bit_cast(float, w.z << 16), __builtin_bit_cast(float, w.z & 0xffff0000u), __builtin_bit_cast(float, w.w << 16), __builtin_bit_cast(float, w.w & 0xffff0000u)} * xi * gi[bj][1]; }
;                     else { b0 = *(const f32x4*)(base + off + bj * HALF); b1 = *(const f32x4*)(base + off + bj * HALF + 4); }
;                     const f32x4 o0 = b0 + acc[ai][bj][m][0], o1 = b1 + acc[ai][bj][m][1];
;                     ss += ((o0[0] * o0[0] + o0[1] * o0[1]) + (o0[2] * o0[2] + o0[3] * o0[3])) + ((o1[0] * o1[0] + o1[1] * o1[1]) + (o1[2] * o1[2] + o1[3] * o1[3]));
;                     u32x4 w2; w2.x = cvt_pk_bf16(o0[0], o0[1]); w2.y = cvt_pk_bf16(o0[2], o0[3]); w2.z = cvt_pk_bf16(o1[0], o1[1]); w2.w = cvt_pk_bf16(o1[2], o1[3]); *(u32x4*)(xb + off + bj * HALF) = w2; }
;                 ss += __shfl_xor(ss, 16); ss += __shfl_xor(ss, 32);
;                 if (fq == 0) stats[(size_t)r * 16 + u.pn * 4 + wc] = ss;
.LBB0_1235:
	s_or_b64 exec, exec, s[30:31]
	v_or_b32_e32 v114, 16, v154
	s_waitcnt lgkmcnt(0)
	v_ashrrev_i32_e32 v115, 31, v114
	v_lshlrev_b64 v[118:119], 11, v[114:115]
	v_lshl_add_u64 v[118:119], s[66:67], 0, v[118:119]
	v_lshl_add_u64 v[174:175], v[144:145], 1, v[118:119]
	s_waitcnt vmcnt(14)
	v_mov_b64 v[118:119], v[210:211]
	v_mov_b64 v[120:121], v[212:213]
	v_lshl_add_u64 v[176:177], v[114:115], 2, s[80:81]
	v_mov_b32_e32 v176, v250
	v_lshlrev_b32_e32 v178, 16, v118
	v_and_b32_e32 v179, 0xffff0000, v118
	v_lshlrev_b32_e32 v118, 16, v119
	v_and_b32_e32 v119, 0xffff0000, v119
	v_lshlrev_b32_e32 v180, 16, v120
	v_and_b32_e32 v181, 0xffff0000, v120
	v_lshlrev_b32_e32 v120, 16, v121
	v_and_b32_e32 v121, 0xffff0000, v121
	v_pk_mul_f32 v[178:179], v[176:177], v[178:179] op_sel_hi:[0,1]
	v_pk_mul_f32 v[118:119], v[176:177], v[118:119] op_sel_hi:[0,1]
	v_pk_mul_f32 v[180:181], v[176:177], v[180:181] op_sel_hi:[0,1]
	v_pk_mul_f32 v[120:121], v[176:177], v[120:121] op_sel_hi:[0,1]
	v_pk_fma_f32 v[118:119], v[152:153], v[118:119], v[112:113]
	v_pk_fma_f32 v[178:179], v[148:149], v[178:179], v[110:111]
	v_pk_fma_f32 v[120:121], v[150:151], v[120:121], v[108:109]
	v_pk_fma_f32 v[180:181], v[146:147], v[180:181], v[106:107]
	v_cvt_pk_bf16_f32 v106, v178, v179
	v_cvt_pk_bf16_f32 v107, v118, v119
	v_mul_f32_e32 v117, v179, v179
	v_cvt_pk_bf16_f32 v108, v180, v181
	v_cvt_pk_bf16_f32 v109, v120, v121
	v_mov_b64 v[110:111], v[214:215]
	v_mov_b64 v[112:113], v[216:217]
	v_add_u32_e32 v203, 0xa0, v154
	v_lshlrev_b32_e32 v204, 2, v203
	v_lshlrev_b32_e32 v203, 11, v203
	v_lshl_add_u32 v203, v144, 1, v203
	global_load_dwordx4 v[210:213], v203, s[66:67]
	global_load_dword v250, v204, s[80:81]
	global_load_dwordx4 v[214:217], v203, s[66:67] offset:256
	v_mul_f32_e32 v119, v119, v119
	v_mul_f32_e32 v155, v181, v181
	v_mul_f32_e32 v121, v121, v121
	v_fmac_f32_e32 v117, v178, v178
	v_fmac_f32_e32 v119, v118, v118
	v_fmac_f32_e32 v155, v180, v180
	v_fmac_f32_e32 v121, v120, v120
	v_add_f32_e32 v117, v117, v119
	v_add_f32_e32 v118, v155, v121
	v_add_f32_e32 v117, v117, v118
	global_store_dwordx4 v[174:175], v[106:109], off
	v_lshlrev_b32_e32 v118, 16, v110
	v_and_b32_e32 v119, 0xffff0000, v110
	v_lshlrev_b32_e32 v110, 16, v111
	v_and_b32_e32 v111, 0xffff0000, v111
	v_lshlrev_b32_e32 v120, 16, v112
	v_and_b32_e32 v121, 0xffff0000, v112
	v_lshlrev_b32_e32 v112, 16, v113
	v_and_b32_e32 v113, 0xffff0000, v113
	v_pk_mul_f32 v[118:119], v[176:177], v[118:119] op_sel_hi:[0,1]
	v_pk_mul_f32 v[110:111], v[176:177], v[110:111] op_sel_hi:[0,1]
	v_pk_mul_f32 v[120:121], v[176:177], v[120:121] op_sel_hi:[0,1]
	v_pk_mul_f32 v[112:113], v[176:177], v[112:113] op_sel_hi:[0,1]
	v_pk_fma_f32 v[104:105], v[128:129], v[110:111], v[104:105]
	v_pk_fma_f32 v[102:103], v[124:125], v[118:119], v[102:103]
	v_pk_fma_f32 v[110:111], v[126:127], v[112:113], v[100:101]
	v_pk_fma_f32 v[112:113], v[122:123], v[120:121], v[98:99]
	v_mul_f32_e32 v98, v103, v103
	v_mul_f32_e32 v99, v105, v105
	v_mul_f32_e32 v100, v113, v113
	v_mul_f32_e32 v101, v111, v111
	v_fmac_f32_e32 v98, v102, v102
	v_fmac_f32_e32 v99, v104, v104
	v_fmac_f32_e32 v100, v112, v112
	v_fmac_f32_e32 v101, v110, v110
	v_add_f32_e32 v98, v98, v99
	v_add_f32_e32 v99, v100, v101
	v_add_f32_e32 v98, v98, v99
	v_add_f32_e32 v98, v117, v98
	ds_bpermute_b32 v99, v172, v98
	v_cvt_pk_bf16_f32 v100, v102, v103
	v_cvt_pk_bf16_f32 v101, v104, v105
	v_cvt_pk_bf16_f32 v102, v112, v113
	v_cvt_pk_bf16_f32 v103, v110, v111
	s_waitcnt lgkmcnt(0)
	v_add_f32_e32 v98, v98, v99
	ds_bpermute_b32 v99, v116, v98
	global_store_dwordx4 v[174:175], v[100:103], off offset:256
	s_and_saveexec_b64 s[30:31], s[6:7]
	s_cbranch_execz .LBB0_1237
	v_lshlrev_b64 v[100:101], 6, v[114:115]
	v_lshl_add_u64 v[100:101], s[8:9], 0, v[100:101]
	v_lshl_add_u64 v[100:101], s[28:29], 2, v[100:101]
	s_lshl_b32 s16, s53, 2
	v_lshl_add_u64 v[100:101], v[100:101], 0, s[16:17]
	s_waitcnt lgkmcnt(0)
	v_add_f32_e32 v98, v98, v99
	global_store_dword v[100:101], v98, off
.LBB0_1237:
	s_or_b64 exec, exec, s[30:31]
	v_or_b32_e32 v98, 32, v154
	s_waitcnt lgkmcnt(0)
	v_ashrrev_i32_e32 v99, 31, v98
	v_lshlrev_b64 v[100:101], 11, v[98:99]
	v_lshl_add_u64 v[100:101], s[66:67], 0, v[100:101]
	v_lshl_add_u64 v[104:105], v[144:145], 1, v[100:101]
	s_waitcnt vmcnt(16)
; __device__ __forceinline__ unsigned cvt_pk_bf16(float lo, float hi) { unsigned r; asm volatile("v_cvt_pk_bf16_f32 %0, %1, %2" : "=v"(r) : "v"(lo), "v"(hi)); return r; }
;     __device__ __forceinline__ void operator()(const f32x4 (&acc)[2][2][4][2], const Unit& u, int wr, int wc, int fr, int fq) const {
;     ...
;         for (int ai = 0; ai < 2; ++ai)
; #pragma unroll
;             for (int m = 0; m < 4; ++m) { const int r = rowt + ai * HALF + wr * 64 + m * 16 + fr; const size_t off = (size_t)r * 1024 + col0; float ss = 0.f;
;                 float xi = 0.f; if constexpr (RECON) xi = xinv[r];
; #pragma unroll
;                 for (int bj = 0; bj < 2; ++bj) { f32x4 b0, b1;
;                     if constexpr (RECON) { const u32x4 w = *(const u32x4*)(xb + off + bj * HALF);
;                         b0 = (f32x4){__builtin_bit_cast(float, w.x << 16), __builtin_bit_cast(float, w.x & 0xffff0000u), __builtin_bit_cast(float, w.y << 16), __builtin_bit_cast(float, w.y & 0xffff0000u)} * xi * gi[bj][0];
;                         b1 = (f32x4){__builtin_bit_cast(float, w.z << 16), __builtin_bit_cast(float, w.z & 0xffff0000u), __builtin_bit_cast(float, w.w << 16), __builtin_bit_cast(float, w.w & 0xffff0000u)} * xi * gi[bj][1]; }
;                     else { b0 = *(const f32x4*)(base + off + bj * HALF); b1 = *(const f32x4*)(base + off + bj * HALF + 4); }
;                     const f32x4 o0 = b0 + acc[ai][bj][m][0], o1 = b1 + acc[ai][bj][m][1];
;                     ss += ((o0[0] * o0[0] + o0[1] * o0[1]) + (o0[2] * o0[2] + o0[3] * o0[3])) + ((o1[0] * o1[0] + o1[1] * o1[1]) + (o1[2] * o1[2] + o1[3] * o1[3]));
;                     u32x4 w2; w2.x = cvt_pk_bf16(o0[0], o0[1]); w2.y = cvt_pk_bf16(o0[2], o0[3]); w2.z = cvt_pk_bf16(o1[0], o1[1]); w2.w = cvt_pk_bf16(o1[2], o1[3]); *(u32x4*)(xb + off + bj * HALF) = w2; }
;                 ss += __shfl_xor(ss, 16); ss += __shfl_xor(ss, 32);
;                 if (fq == 0) stats[(size_t)r * 16 + u.pn * 4 + wc] = ss;
	v_mov_b64 v[100:101], v[218:219]
	v_mov_b64 v[102:103], v[220:221]
	v_lshl_add_u64 v[106:107], v[98:99], 2, s[80:81]
	v_mov_b32_e32 v106, v251
	v_lshlrev_b32_e32 v108, 16, v100
	v_and_b32_e32 v109, 0xffff0000, v100
	v_lshlrev_b32_e32 v100, 16, v101
	v_and_b32_e32 v101, 0xffff0000, v101
	v_lshlrev_b32_e32 v110, 16, v102
	v_and_b32_e32 v111, 0xffff0000, v102
	v_lshlrev_b32_e32 v102, 16, v103
	v_and_b32_e32 v103, 0xffff0000, v103
	v_pk_mul_f32 v[108:109], v[106:107], v[108:109] op_sel_hi:[0,1]
	v_pk_mul_f32 v[100:101], v[106:107], v[100:101] op_sel_hi:[0,1]
	v_pk_mul_f32 v[110:111], v[106:107], v[110:111] op_sel_hi:[0,1]
	v_pk_mul_f32 v[102:103], v[106:107], v[102:103] op_sel_hi:[0,1]
	v_pk_fma_f32 v[100:101], v[152:153], v[100:101], v[96:97]
	v_pk_fma_f32 v[108:109], v[148:149], v[108:109], v[94:95]
	v_pk_fma_f32 v[102:103], v[150:151], v[102:103], v[92:93]
	v_pk_fma_f32 v[110:111], v[146:147], v[110:111], v[90:91]
	v_cvt_pk_bf16_f32 v90, v108, v109
	v_cvt_pk_bf16_f32 v91, v100, v101
	v_mul_f32_e32 v107, v109, v109
	v_cvt_pk_bf16_f32 v92, v110, v111
	v_cvt_pk_bf16_f32 v93, v102, v103
	v_mov_b64 v[94:95], v[222:223]
	v_mov_b64 v[96:97], v[224:225]
	v_add_u32_e32 v203, 0xb0, v154
	v_lshlrev_b32_e32 v204, 2, v203
	v_lshlrev_b32_e32 v203, 11, v203
	v_lshl_add_u32 v203, v144, 1, v203
	global_load_dwordx4 v[218:221], v203, s[66:67]
	global_load_dword v251, v204, s[80:81]
	global_load_dwordx4 v[222:225], v203, s[66:67] offset:256
	v_mul_f32_e32 v101, v101, v101
	v_mul_f32_e32 v109, v111, v111
	v_mul_f32_e32 v103, v103, v103
	v_fmac_f32_e32 v107, v108, v108
	v_fmac_f32_e32 v101, v100, v100
	v_fmac_f32_e32 v109, v110, v110
	v_fmac_f32_e32 v103, v102, v102
	v_add_f32_e32 v100, v107, v101
	v_add_f32_e32 v101, v109, v103
	v_add_f32_e32 v107, v100, v101
	global_store_dwordx4 v[104:105], v[90:93], off
	v_lshlrev_b32_e32 v100, 16, v94
	v_and_b32_e32 v101, 0xffff0000, v94
	v_lshlrev_b32_e32 v94, 16, v95
	v_and_b32_e32 v95, 0xffff0000, v95
	v_lshlrev_b32_e32 v102, 16, v96
	v_and_b32_e32 v103, 0xffff0000, v96
	v_lshlrev_b32_e32 v96, 16, v97
	v_and_b32_e32 v97, 0xffff0000, v97
	v_pk_mul_f32 v[100:101], v[106:107], v[100:101] op_sel_hi:[0,1]
	v_pk_mul_f32 v[94:95], v[106:107], v[94:95] op_sel_hi:[0,1]
	v_pk_mul_f32 v[102:103], v[106:107], v[102:103] op_sel_hi:[0,1]
	v_pk_mul_f32 v[96:97], v[106:107], v[96:97] op_sel_hi:[0,1]
	v_pk_fma_f32 v[88:89], v[128:129], v[94:95], v[88:89]
	v_pk_fma_f32 v[86:87], v[124:125], v[100:101], v[86:87]
	v_pk_fma_f32 v[94:95], v[126:127], v[96:97], v[84:85]
	v_pk_fma_f32 v[96:97], v[122:123], v[102:103], v[82:83]
	v_mul_f32_e32 v82, v87, v87
	v_mul_f32_e32 v83, v89, v89
	v_mul_f32_e32 v84, v97, v97
	v_mul_f32_e32 v85, v95, v95
	v_fmac_f32_e32 v82, v86, v86
	v_fmac_f32_e32 v83, v88, v88
	v_fmac_f32_e32 v84, v96, v96
	v_fmac_f32_e32 v85, v94, v94
	v_add_f32_e32 v82, v82, v83
	v_add_f32_e32 v83, v84, v85
	v_add_f32_e32 v82, v82, v83
	v_add_f32_e32 v82, v107, v82
	ds_bpermute_b32 v83, v172, v82
	v_cvt_pk_bf16_f32 v84, v86, v87
	v_cvt_pk_bf16_f32 v85, v88, v89
	v_cvt_pk_bf16_f32 v86, v96, v97
	v_cvt_pk_bf16_f32 v87, v94, v95
	s_waitcnt lgkmcnt(0)
	v_add_f32_e32 v82, v82, v83
	ds_bpermute_b32 v83, v116, v82
	global_store_dwordx4 v[104:105], v[84:87], off offset:256
	s_and_saveexec_b64 s[30:31], s[6:7]
	s_cbranch_execz .LBB0_1239
	v_lshlrev_b64 v[84:85], 6, v[98:99]
	v_lshl_add_u64 v[84:85], s[8:9], 0, v[84:85]
	v_lshl_add_u64 v[84:85], s[28:29], 2, v[84:85]
	s_lshl_b32 s16, s53, 2
	v_lshl_add_u64 v[84:85], v[84:85], 0, s[16:17]
	s_waitcnt lgkmcnt(0)
	v_add_f32_e32 v82, v82, v83
	global_store_dword v[84:85], v82, off
.LBB0_1239:
	s_or_b64 exec, exec, s[30:31]
	v_or_b32_e32 v82, 48, v154
	s_waitcnt lgkmcnt(0)
	v_ashrrev_i32_e32 v83, 31, v82
	v_lshlrev_b64 v[84:85], 11, v[82:83]
	v_lshl_add_u64 v[84:85], s[66:67], 0, v[84:85]
	v_lshl_add_u64 v[88:89], v[144:145], 1, v[84:85]
	s_waitcnt vmcnt(18)
	v_mov_b64 v[84:85], v[226:227]
	v_mov_b64 v[86:87], v[228:229]
	v_lshl_add_u64 v[90:91], v[82:83], 2, s[80:81]
	v_mov_b32_e32 v90, v252
	v_lshlrev_b32_e32 v92, 16, v84
	v_and_b32_e32 v93, 0xffff0000, v84
	v_lshlrev_b32_e32 v84, 16, v85
	v_and_b32_e32 v85, 0xffff0000, v85
	v_lshlrev_b32_e32 v94, 16, v86
	v_and_b32_e32 v95, 0xffff0000, v86
	v_lshlrev_b32_e32 v86, 16, v87
	v_and_b32_e32 v87, 0xffff0000, v87
	v_pk_mul_f32 v[92:93], v[90:91], v[92:93] op_sel_hi:[0,1]
	v_pk_mul_f32 v[84:85], v[90:91], v[84:85] op_sel_hi:[0,1]
	v_pk_mul_f32 v[94:95], v[90:91], v[94:95] op_sel_hi:[0,1]
	v_pk_mul_f32 v[86:87], v[90:91], v[86:87] op_sel_hi:[0,1]
	v_pk_fma_f32 v[84:85], v[152:153], v[84:85], v[80:81]
	v_pk_fma_f32 v[92:93], v[148:149], v[92:93], v[78:79]
	v_pk_fma_f32 v[86:87], v[150:151], v[86:87], v[76:77]
	v_pk_fma_f32 v[94:95], v[146:147], v[94:95], v[74:75]
	v_cvt_pk_bf16_f32 v74, v92, v93
	v_cvt_pk_bf16_f32 v75, v84, v85
	v_mul_f32_e32 v91, v93, v93
	v_cvt_pk_bf16_f32 v76, v94, v95
	v_cvt_pk_bf16_f32 v77, v86, v87
	v_mov_b64 v[78:79], v[230:231]
	v_mov_b64 v[80:81], v[232:233]
	v_mul_f32_e32 v85, v85, v85
	v_mul_f32_e32 v93, v95, v95
	v_mul_f32_e32 v87, v87, v87
	v_fmac_f32_e32 v91, v92, v92
	v_fmac_f32_e32 v85, v84, v84
	v_fmac_f32_e32 v93, v94, v94
	v_fmac_f32_e32 v87, v86, v86
	v_add_f32_e32 v84, v91, v85
	v_add_f32_e32 v85, v93, v87
	v_add_f32_e32 v91, v84, v85
	global_store_dwordx4 v[88:89], v[74:77], off
	v_lshlrev_b32_e32 v84, 16, v78
	v_and_b32_e32 v85, 0xffff0000, v78
	v_lshlrev_b32_e32 v78, 16, v79
	v_and_b32_e32 v79, 0xffff0000, v79
	v_lshlrev_b32_e32 v86, 16, v80
	v_and_b32_e32 v87, 0xffff0000, v80
	v_lshlrev_b32_e32 v80, 16, v81
	v_and_b32_e32 v81, 0xffff0000, v81
	v_pk_mul_f32 v[84:85], v[90:91], v[84:85] op_sel_hi:[0,1]
	v_pk_mul_f32 v[78:79], v[90:91], v[78:79] op_sel_hi:[0,1]
	v_pk_mul_f32 v[86:87], v[90:91], v[86:87] op_sel_hi:[0,1]
	v_pk_mul_f32 v[80:81], v[90:91], v[80:81] op_sel_hi:[0,1]
	v_pk_fma_f32 v[72:73], v[128:129], v[78:79], v[72:73]
	v_pk_fma_f32 v[70:71], v[124:125], v[84:85], v[70:71]
	v_pk_fma_f32 v[78:79], v[126:127], v[80:81], v[68:69]
	v_pk_fma_f32 v[80:81], v[122:123], v[86:87], v[66:67]
	v_mul_f32_e32 v66, v71, v71
	v_mul_f32_e32 v67, v73, v73
	v_mul_f32_e32 v68, v81, v81
	v_mul_f32_e32 v69, v79, v79
	v_fmac_f32_e32 v66, v70, v70
	v_fmac_f32_e32 v67, v72, v72
	v_fmac_f32_e32 v68, v80, v80
	v_fmac_f32_e32 v69, v78, v78
	v_add_f32_e32 v66, v66, v67
	v_add_f32_e32 v67, v68, v69
	v_add_f32_e32 v66, v66, v67
	v_add_f32_e32 v66, v91, v66
	ds_bpermute_b32 v67, v172, v66
	v_cvt_pk_bf16_f32 v68, v70, v71
	v_cvt_pk_bf16_f32 v69, v72, v73
	v_cvt_pk_bf16_f32 v70, v80, v81
	v_cvt_pk_bf16_f32 v71, v78, v79
	s_waitcnt lgkmcnt(0)
	v_add_f32_e32 v66, v66, v67
	ds_bpermute_b32 v67, v116, v66
	global_store_dwordx4 v[88:89], v[68:71], off offset:256
	s_and_saveexec_b64 s[30:31], s[6:7]
	s_cbranch_execz .LBB0_1241
	v_lshlrev_b64 v[68:69], 6, v[82:83]
	v_lshl_add_u64 v[68:69], s[8:9], 0, v[68:69]
	v_lshl_add_u64 v[68:69], s[28:29], 2, v[68:69]
	s_lshl_b32 s16, s53, 2
	v_lshl_add_u64 v[68:69], v[68:69], 0, s[16:17]
	s_waitcnt lgkmcnt(0)
	v_add_f32_e32 v66, v66, v67
	global_store_dword v[68:69], v66, off
; __device__ __forceinline__ unsigned cvt_pk_bf16(float lo, float hi) { unsigned r; asm volatile("v_cvt_pk_bf16_f32 %0, %1, %2" : "=v"(r) : "v"(lo), "v"(hi)); return r; }
;     __device__ __forceinline__ void operator()(const f32x4 (&acc)[2][2][4][2], const Unit& u, int wr, int wc, int fr, int fq) const {
;     ...
;         for (int ai = 0; ai < 2; ++ai)
; #pragma unroll
;             for (int m = 0; m < 4; ++m) { const int r = rowt + ai * HALF + wr * 64 + m * 16 + fr; const size_t off = (size_t)r * 1024 + col0; float ss = 0.f;
;                 float xi = 0.f; if constexpr (RECON) xi = xinv[r];
; #pragma unroll
;                 for (int bj = 0; bj < 2; ++bj) { f32x4 b0, b1;
;                     if constexpr (RECON) { const u32x4 w = *(const u32x4*)(xb + off + bj * HALF);
;                         b0 = (f32x4){__builtin_bit_cast(float, w.x << 16), __builtin_bit_cast(float, w.x & 0xffff0000u), __builtin_bit_cast(float, w.y << 16), __builtin_bit_cast(float, w.y & 0xffff0000u)} * xi * gi[bj][0];
;                         b1 = (f32x4){__builtin_bit_cast(float, w.z << 16), __builtin_bit_cast(float, w.z & 0xffff0000u), __builtin_bit_cast(float, w.w << 16), __builtin_bit_cast(float, w.w & 0xffff0000u)} * xi * gi[bj][1]; }
;                     else { b0 = *(const f32x4*)(base + off + bj * HALF); b1 = *(const f32x4*)(base + off + bj * HALF + 4); }
;                     const f32x4 o0 = b0 + acc[ai][bj][m][0], o1 = b1 + acc[ai][bj][m][1];
;                     ss += ((o0[0] * o0[0] + o0[1] * o0[1]) + (o0[2] * o0[2] + o0[3] * o0[3])) + ((o1[0] * o1[0] + o1[1] * o1[1]) + (o1[2] * o1[2] + o1[3] * o1[3]));
;                     u32x4 w2; w2.x = cvt_pk_bf16(o0[0], o0[1]); w2.y = cvt_pk_bf16(o0[2], o0[3]); w2.z = cvt_pk_bf16(o1[0], o1[1]); w2.w = cvt_pk_bf16(o1[2], o1[3]); *(u32x4*)(xb + off + bj * HALF) = w2; }
;                 ss += __shfl_xor(ss, 16); ss += __shfl_xor(ss, 32);
;                 if (fq == 0) stats[(size_t)r * 16 + u.pn * 4 + wc] = ss;
.LBB0_1241:
	s_or_b64 exec, exec, s[30:31]
	v_add_u32_e32 v66, 0x80, v154
	s_waitcnt lgkmcnt(0)
	v_ashrrev_i32_e32 v67, 31, v66
	v_lshlrev_b64 v[68:69], 11, v[66:67]
	v_lshl_add_u64 v[68:69], s[66:67], 0, v[68:69]
	v_lshl_add_u64 v[72:73], v[144:145], 1, v[68:69]
	s_waitcnt vmcnt(17)
	v_mov_b64 v[68:69], v[234:235]
	v_mov_b64 v[70:71], v[236:237]
	v_lshl_add_u64 v[74:75], v[66:67], 2, s[80:81]
	v_mov_b32_e32 v74, v253
	v_lshlrev_b32_e32 v76, 16, v68
	v_and_b32_e32 v77, 0xffff0000, v68
	v_lshlrev_b32_e32 v68, 16, v69
	v_and_b32_e32 v69, 0xffff0000, v69
	v_lshlrev_b32_e32 v78, 16, v70
	v_and_b32_e32 v79, 0xffff0000, v70
	v_lshlrev_b32_e32 v70, 16, v71
	v_and_b32_e32 v71, 0xffff0000, v71
	v_pk_mul_f32 v[76:77], v[74:75], v[76:77] op_sel_hi:[0,1]
	v_pk_mul_f32 v[68:69], v[74:75], v[68:69] op_sel_hi:[0,1]
	v_pk_mul_f32 v[78:79], v[74:75], v[78:79] op_sel_hi:[0,1]
	v_pk_mul_f32 v[70:71], v[74:75], v[70:71] op_sel_hi:[0,1]
	v_pk_fma_f32 v[68:69], v[152:153], v[68:69], v[64:65]
	v_pk_fma_f32 v[76:77], v[148:149], v[76:77], v[62:63]
	v_pk_fma_f32 v[70:71], v[150:151], v[70:71], v[60:61]
	v_pk_fma_f32 v[78:79], v[146:147], v[78:79], v[58:59]
	v_cvt_pk_bf16_f32 v58, v76, v77
	v_cvt_pk_bf16_f32 v59, v68, v69
	v_mul_f32_e32 v75, v77, v77
	v_cvt_pk_bf16_f32 v60, v78, v79
	v_cvt_pk_bf16_f32 v61, v70, v71
	v_mov_b64 v[62:63], v[238:239]
	v_mov_b64 v[64:65], v[240:241]
	v_mul_f32_e32 v69, v69, v69
	v_mul_f32_e32 v77, v79, v79
	v_mul_f32_e32 v71, v71, v71
	v_fmac_f32_e32 v75, v76, v76
	v_fmac_f32_e32 v69, v68, v68
	v_fmac_f32_e32 v77, v78, v78
	v_fmac_f32_e32 v71, v70, v70
	v_add_f32_e32 v68, v75, v69
	v_add_f32_e32 v69, v77, v71
	v_add_f32_e32 v75, v68, v69
	global_store_dwordx4 v[72:73], v[58:61], off
	v_lshlrev_b32_e32 v68, 16, v62
	v_and_b32_e32 v69, 0xffff0000, v62
	v_lshlrev_b32_e32 v62, 16, v63
	v_and_b32_e32 v63, 0xffff0000, v63
	v_lshlrev_b32_e32 v70, 16, v64
	v_and_b32_e32 v71, 0xffff0000, v64
	v_lshlrev_b32_e32 v64, 16, v65
	v_and_b32_e32 v65, 0xffff0000, v65
	v_pk_mul_f32 v[68:69], v[74:75], v[68:69] op_sel_hi:[0,1]
	v_pk_mul_f32 v[62:63], v[74:75], v[62:63] op_sel_hi:[0,1]
	v_pk_mul_f32 v[70:71], v[74:75], v[70:71] op_sel_hi:[0,1]
	v_pk_mul_f32 v[64:65], v[74:75], v[64:65] op_sel_hi:[0,1]
	v_pk_fma_f32 v[56:57], v[128:129], v[62:63], v[56:57]
	v_pk_fma_f32 v[54:55], v[124:125], v[68:69], v[54:55]
	v_pk_fma_f32 v[62:63], v[126:127], v[64:65], v[52:53]
	v_pk_fma_f32 v[64:65], v[122:123], v[70:71], v[50:51]
	v_mul_f32_e32 v50, v55, v55
	v_mul_f32_e32 v51, v57, v57
	v_mul_f32_e32 v52, v65, v65
	v_mul_f32_e32 v53, v63, v63
	v_fmac_f32_e32 v50, v54, v54
	v_fmac_f32_e32 v51, v56, v56
	v_fmac_f32_e32 v52, v64, v64
	v_fmac_f32_e32 v53, v62, v62
	v_add_f32_e32 v50, v50, v51
	v_add_f32_e32 v51, v52, v53
	v_add_f32_e32 v50, v50, v51
	v_add_f32_e32 v50, v75, v50
	ds_bpermute_b32 v51, v172, v50
	v_cvt_pk_bf16_f32 v52, v54, v55
	v_cvt_pk_bf16_f32 v53, v56, v57
	v_cvt_pk_bf16_f32 v54, v64, v65
	v_cvt_pk_bf16_f32 v55, v62, v63
	s_waitcnt lgkmcnt(0)
	v_add_f32_e32 v50, v50, v51
	ds_bpermute_b32 v51, v116, v50
	global_store_dwordx4 v[72:73], v[52:55], off offset:256
	s_and_saveexec_b64 s[30:31], s[6:7]
	s_cbranch_execz .LBB0_1243
	v_lshlrev_b64 v[52:53], 6, v[66:67]
	v_lshl_add_u64 v[52:53], s[8:9], 0, v[52:53]
	v_lshl_add_u64 v[52:53], s[28:29], 2, v[52:53]
	s_lshl_b32 s16, s53, 2
	v_lshl_add_u64 v[52:53], v[52:53], 0, s[16:17]
	s_waitcnt lgkmcnt(0)
	v_add_f32_e32 v50, v50, v51
	global_store_dword v[52:53], v50, off
.LBB0_1243:
	s_or_b64 exec, exec, s[30:31]
	v_add_u32_e32 v50, 0x90, v154
	s_waitcnt lgkmcnt(0)
	v_ashrrev_i32_e32 v51, 31, v50
	v_lshlrev_b64 v[52:53], 11, v[50:51]
	v_lshl_add_u64 v[52:53], s[66:67], 0, v[52:53]
	v_lshl_add_u64 v[56:57], v[144:145], 1, v[52:53]
	s_waitcnt vmcnt(16)
	v_mov_b64 v[52:53], v[242:243]
	v_mov_b64 v[54:55], v[244:245]
	v_lshl_add_u64 v[58:59], v[50:51], 2, s[80:81]
	v_mov_b32_e32 v58, v202
	v_lshlrev_b32_e32 v60, 16, v52
	v_and_b32_e32 v61, 0xffff0000, v52
	v_lshlrev_b32_e32 v52, 16, v53
	v_and_b32_e32 v53, 0xffff0000, v53
	v_lshlrev_b32_e32 v62, 16, v54
	v_and_b32_e32 v63, 0xffff0000, v54
	v_lshlrev_b32_e32 v54, 16, v55
	v_and_b32_e32 v55, 0xffff0000, v55
	v_pk_mul_f32 v[60:61], v[58:59], v[60:61] op_sel_hi:[0,1]
	v_pk_mul_f32 v[52:53], v[58:59], v[52:53] op_sel_hi:[0,1]
	v_pk_mul_f32 v[62:63], v[58:59], v[62:63] op_sel_hi:[0,1]
	v_pk_mul_f32 v[54:55], v[58:59], v[54:55] op_sel_hi:[0,1]
	v_pk_fma_f32 v[52:53], v[152:153], v[52:53], v[48:49]
	v_pk_fma_f32 v[60:61], v[148:149], v[60:61], v[46:47]
	v_pk_fma_f32 v[54:55], v[150:151], v[54:55], v[44:45]
	v_pk_fma_f32 v[62:63], v[146:147], v[62:63], v[42:43]
	v_cvt_pk_bf16_f32 v42, v60, v61
	v_cvt_pk_bf16_f32 v43, v52, v53
	v_mul_f32_e32 v59, v61, v61
	v_cvt_pk_bf16_f32 v44, v62, v63
	v_cvt_pk_bf16_f32 v45, v54, v55
	v_mov_b64 v[46:47], v[246:247]
	v_mov_b64 v[48:49], v[248:249]
	v_mul_f32_e32 v53, v53, v53
	v_mul_f32_e32 v61, v63, v63
	v_mul_f32_e32 v55, v55, v55
	v_fmac_f32_e32 v59, v60, v60
	v_fmac_f32_e32 v53, v52, v52
	v_fmac_f32_e32 v61, v62, v62
	v_fmac_f32_e32 v55, v54, v54
	v_add_f32_e32 v52, v59, v53
	v_add_f32_e32 v53, v61, v55
	v_add_f32_e32 v59, v52, v53
	global_store_dwordx4 v[56:57], v[42:45], off
	v_lshlrev_b32_e32 v52, 16, v46
	v_and_b32_e32 v53, 0xffff0000, v46
	v_lshlrev_b32_e32 v46, 16, v47
	v_and_b32_e32 v47, 0xffff0000, v47
	v_lshlrev_b32_e32 v54, 16, v48
	v_and_b32_e32 v55, 0xffff0000, v48
	v_lshlrev_b32_e32 v48, 16, v49
	v_and_b32_e32 v49, 0xffff0000, v49
	v_pk_mul_f32 v[52:53], v[58:59], v[52:53] op_sel_hi:[0,1]
	v_pk_mul_f32 v[46:47], v[58:59], v[46:47] op_sel_hi:[0,1]
	v_pk_mul_f32 v[54:55], v[58:59], v[54:55] op_sel_hi:[0,1]
	v_pk_mul_f32 v[48:49], v[58:59], v[48:49] op_sel_hi:[0,1]
	v_pk_fma_f32 v[40:41], v[128:129], v[46:47], v[40:41]
	v_pk_fma_f32 v[38:39], v[124:125], v[52:53], v[38:39]
	v_pk_fma_f32 v[46:47], v[126:127], v[48:49], v[36:37]
	v_pk_fma_f32 v[48:49], v[122:123], v[54:55], v[34:35]
	v_mul_f32_e32 v34, v39, v39
	v_mul_f32_e32 v35, v41, v41
	v_mul_f32_e32 v36, v49, v49
	v_mul_f32_e32 v37, v47, v47
	v_fmac_f32_e32 v34, v38, v38
	v_fmac_f32_e32 v35, v40, v40
	v_fmac_f32_e32 v36, v48, v48
	v_fmac_f32_e32 v37, v46, v46
	v_add_f32_e32 v34, v34, v35
	v_add_f32_e32 v35, v36, v37
	v_add_f32_e32 v34, v34, v35
	v_add_f32_e32 v34, v59, v34
	ds_bpermute_b32 v35, v172, v34
	v_cvt_pk_bf16_f32 v36, v38, v39
	v_cvt_pk_bf16_f32 v37, v40, v41
	v_cvt_pk_bf16_f32 v38, v48, v49
	v_cvt_pk_bf16_f32 v39, v46, v47
	s_waitcnt lgkmcnt(0)
	v_add_f32_e32 v34, v34, v35
	ds_bpermute_b32 v35, v116, v34
	global_store_dwordx4 v[56:57], v[36:39], off offset:256
	s_and_saveexec_b64 s[30:31], s[6:7]
	s_cbranch_execz .LBB0_1245
	v_lshlrev_b64 v[36:37], 6, v[50:51]
	v_lshl_add_u64 v[36:37], s[8:9], 0, v[36:37]
	v_lshl_add_u64 v[36:37], s[28:29], 2, v[36:37]
	s_lshl_b32 s16, s53, 2
	v_lshl_add_u64 v[36:37], v[36:37], 0, s[16:17]
	s_waitcnt lgkmcnt(0)
	v_add_f32_e32 v34, v34, v35
	global_store_dword v[36:37], v34, off
; __device__ __forceinline__ unsigned cvt_pk_bf16(float lo, float hi) { unsigned r; asm volatile("v_cvt_pk_bf16_f32 %0, %1, %2" : "=v"(r) : "v"(lo), "v"(hi)); return r; }
;     __device__ __forceinline__ void operator()(const f32x4 (&acc)[2][2][4][2], const Unit& u, int wr, int wc, int fr, int fq) const {
;     ...
;         for (int ai = 0; ai < 2; ++ai)
; #pragma unroll
;             for (int m = 0; m < 4; ++m) { const int r = rowt + ai * HALF + wr * 64 + m * 16 + fr; const size_t off = (size_t)r * 1024 + col0; float ss = 0.f;
;                 float xi = 0.f; if constexpr (RECON) xi = xinv[r];
; #pragma unroll
;                 for (int bj = 0; bj < 2; ++bj) { f32x4 b0, b1;
;                     if constexpr (RECON) { const u32x4 w = *(const u32x4*)(xb + off + bj * HALF);
;                         b0 = (f32x4){__builtin_bit_cast(float, w.x << 16), __builtin_bit_cast(float, w.x & 0xffff0000u), __builtin_bit_cast(float, w.y << 16), __builtin_bit_cast(float, w.y & 0xffff0000u)} * xi * gi[bj][0];
;                         b1 = (f32x4){__builtin_bit_cast(float, w.z << 16), __builtin_bit_cast(float, w.z & 0xffff0000u), __builtin_bit_cast(float, w.w << 16), __builtin_bit_cast(float, w.w & 0xffff0000u)} * xi * gi[bj][1]; }
;                     else { b0 = *(const f32x4*)(base + off + bj * HALF); b1 = *(const f32x4*)(base + off + bj * HALF + 4); }
;                     const f32x4 o0 = b0 + acc[ai][bj][m][0], o1 = b1 + acc[ai][bj][m][1];
;                     ss += ((o0[0] * o0[0] + o0[1] * o0[1]) + (o0[2] * o0[2] + o0[3] * o0[3])) + ((o1[0] * o1[0] + o1[1] * o1[1]) + (o1[2] * o1[2] + o1[3] * o1[3]));
;                     u32x4 w2; w2.x = cvt_pk_bf16(o0[0], o0[1]); w2.y = cvt_pk_bf16(o0[2], o0[3]); w2.z = cvt_pk_bf16(o1[0], o1[1]); w2.w = cvt_pk_bf16(o1[2], o1[3]); *(u32x4*)(xb + off + bj * HALF) = w2; }
;                 ss += __shfl_xor(ss, 16); ss += __shfl_xor(ss, 32);
;                 if (fq == 0) stats[(size_t)r * 16 + u.pn * 4 + wc] = ss;
.LBB0_1245:
	s_or_b64 exec, exec, s[30:31]
	v_add_u32_e32 v34, 0xa0, v154
	s_waitcnt lgkmcnt(0)
	v_ashrrev_i32_e32 v35, 31, v34
	v_lshlrev_b64 v[36:37], 11, v[34:35]
	v_lshl_add_u64 v[36:37], s[66:67], 0, v[36:37]
	v_lshl_add_u64 v[40:41], v[144:145], 1, v[36:37]
	s_waitcnt vmcnt(13)
	v_mov_b64 v[36:37], v[210:211]
	v_mov_b64 v[38:39], v[212:213]
	v_lshl_add_u64 v[42:43], v[34:35], 2, s[80:81]
	v_mov_b32_e32 v42, v250
	v_lshlrev_b32_e32 v44, 16, v36
	v_and_b32_e32 v45, 0xffff0000, v36
	v_lshlrev_b32_e32 v36, 16, v37
	v_and_b32_e32 v37, 0xffff0000, v37
	v_lshlrev_b32_e32 v46, 16, v38
	v_and_b32_e32 v47, 0xffff0000, v38
	v_lshlrev_b32_e32 v38, 16, v39
	v_and_b32_e32 v39, 0xffff0000, v39
	v_pk_mul_f32 v[44:45], v[42:43], v[44:45] op_sel_hi:[0,1]
	v_pk_mul_f32 v[36:37], v[42:43], v[36:37] op_sel_hi:[0,1]
	v_pk_mul_f32 v[46:47], v[42:43], v[46:47] op_sel_hi:[0,1]
	v_pk_mul_f32 v[38:39], v[42:43], v[38:39] op_sel_hi:[0,1]
	v_pk_fma_f32 v[36:37], v[152:153], v[36:37], v[32:33]
	v_pk_fma_f32 v[44:45], v[148:149], v[44:45], v[30:31]
	v_pk_fma_f32 v[38:39], v[150:151], v[38:39], v[28:29]
	v_pk_fma_f32 v[46:47], v[146:147], v[46:47], v[26:27]
	v_cvt_pk_bf16_f32 v26, v44, v45
	v_cvt_pk_bf16_f32 v27, v36, v37
	v_mul_f32_e32 v43, v45, v45
	v_cvt_pk_bf16_f32 v28, v46, v47
	v_cvt_pk_bf16_f32 v29, v38, v39
	v_mov_b64 v[30:31], v[214:215]
	v_mov_b64 v[32:33], v[216:217]
	v_mul_f32_e32 v37, v37, v37
	v_mul_f32_e32 v45, v47, v47
	v_mul_f32_e32 v39, v39, v39
	v_fmac_f32_e32 v43, v44, v44
	v_fmac_f32_e32 v37, v36, v36
	v_fmac_f32_e32 v45, v46, v46
	v_fmac_f32_e32 v39, v38, v38
	v_add_f32_e32 v36, v43, v37
	v_add_f32_e32 v37, v45, v39
	v_add_f32_e32 v43, v36, v37
	global_store_dwordx4 v[40:41], v[26:29], off
	v_lshlrev_b32_e32 v36, 16, v30
	v_and_b32_e32 v37, 0xffff0000, v30
	v_lshlrev_b32_e32 v30, 16, v31
	v_and_b32_e32 v31, 0xffff0000, v31
	v_lshlrev_b32_e32 v38, 16, v32
	v_and_b32_e32 v39, 0xffff0000, v32
	v_lshlrev_b32_e32 v32, 16, v33
	v_and_b32_e32 v33, 0xffff0000, v33
	v_pk_mul_f32 v[36:37], v[42:43], v[36:37] op_sel_hi:[0,1]
	v_pk_mul_f32 v[30:31], v[42:43], v[30:31] op_sel_hi:[0,1]
	v_pk_mul_f32 v[38:39], v[42:43], v[38:39] op_sel_hi:[0,1]
	v_pk_mul_f32 v[32:33], v[42:43], v[32:33] op_sel_hi:[0,1]
	v_pk_fma_f32 v[24:25], v[128:129], v[30:31], v[24:25]
	v_pk_fma_f32 v[22:23], v[124:125], v[36:37], v[22:23]
	v_pk_fma_f32 v[30:31], v[126:127], v[32:33], v[20:21]
	v_pk_fma_f32 v[32:33], v[122:123], v[38:39], v[18:19]
	v_mul_f32_e32 v18, v23, v23
	v_mul_f32_e32 v19, v25, v25
	v_mul_f32_e32 v20, v33, v33
	v_mul_f32_e32 v21, v31, v31
	v_fmac_f32_e32 v18, v22, v22
	v_fmac_f32_e32 v19, v24, v24
	v_fmac_f32_e32 v20, v32, v32
	v_fmac_f32_e32 v21, v30, v30
	v_add_f32_e32 v18, v18, v19
	v_add_f32_e32 v19, v20, v21
	v_add_f32_e32 v18, v18, v19
	v_add_f32_e32 v18, v43, v18
	ds_bpermute_b32 v19, v172, v18
	v_cvt_pk_bf16_f32 v20, v22, v23
	v_cvt_pk_bf16_f32 v21, v24, v25
	v_cvt_pk_bf16_f32 v22, v32, v33
	v_cvt_pk_bf16_f32 v23, v30, v31
	s_waitcnt lgkmcnt(0)
	v_add_f32_e32 v18, v18, v19
	ds_bpermute_b32 v19, v116, v18
	global_store_dwordx4 v[40:41], v[20:23], off offset:256
	s_and_saveexec_b64 s[30:31], s[6:7]
	s_cbranch_execz .LBB0_1247
	v_lshlrev_b64 v[20:21], 6, v[34:35]
	v_lshl_add_u64 v[20:21], s[8:9], 0, v[20:21]
	v_lshl_add_u64 v[20:21], s[28:29], 2, v[20:21]
	s_lshl_b32 s16, s53, 2
	v_lshl_add_u64 v[20:21], v[20:21], 0, s[16:17]
	s_waitcnt lgkmcnt(0)
	v_add_f32_e32 v18, v18, v19
	global_store_dword v[20:21], v18, off
.LBB0_1247:
	s_or_b64 exec, exec, s[30:31]
	v_add_u32_e32 v18, 0xb0, v154
	s_waitcnt lgkmcnt(0)
	v_ashrrev_i32_e32 v19, 31, v18
	v_lshlrev_b64 v[20:21], 11, v[18:19]
	v_lshl_add_u64 v[20:21], s[66:67], 0, v[20:21]
	v_lshl_add_u64 v[24:25], v[144:145], 1, v[20:21]
	s_waitcnt vmcnt(10)
	v_mov_b64 v[20:21], v[218:219]
	v_mov_b64 v[22:23], v[220:221]
	v_lshl_add_u64 v[26:27], v[18:19], 2, s[80:81]
	v_mov_b32_e32 v26, v251
	v_lshlrev_b32_e32 v28, 16, v20
	v_and_b32_e32 v29, 0xffff0000, v20
	v_lshlrev_b32_e32 v20, 16, v21
	v_and_b32_e32 v21, 0xffff0000, v21
	v_lshlrev_b32_e32 v30, 16, v22
	v_and_b32_e32 v31, 0xffff0000, v22
	v_lshlrev_b32_e32 v22, 16, v23
	v_and_b32_e32 v23, 0xffff0000, v23
	v_pk_mul_f32 v[28:29], v[26:27], v[28:29] op_sel_hi:[0,1]
	v_pk_mul_f32 v[20:21], v[26:27], v[20:21] op_sel_hi:[0,1]
	v_pk_mul_f32 v[30:31], v[26:27], v[30:31] op_sel_hi:[0,1]
	v_pk_mul_f32 v[22:23], v[26:27], v[22:23] op_sel_hi:[0,1]
	v_pk_fma_f32 v[20:21], v[152:153], v[20:21], v[16:17]
	v_pk_fma_f32 v[28:29], v[148:149], v[28:29], v[14:15]
	v_pk_fma_f32 v[22:23], v[150:151], v[22:23], v[12:13]
	v_pk_fma_f32 v[30:31], v[146:147], v[30:31], v[10:11]
	v_cvt_pk_bf16_f32 v10, v28, v29
	v_cvt_pk_bf16_f32 v11, v20, v21
	v_mul_f32_e32 v27, v29, v29
	v_cvt_pk_bf16_f32 v12, v30, v31
	v_cvt_pk_bf16_f32 v13, v22, v23
	v_mov_b64 v[14:15], v[222:223]
	v_mov_b64 v[16:17], v[224:225]
	v_mul_f32_e32 v21, v21, v21
	v_mul_f32_e32 v29, v31, v31
	v_mul_f32_e32 v23, v23, v23
	v_fmac_f32_e32 v27, v28, v28
	v_fmac_f32_e32 v21, v20, v20
	v_fmac_f32_e32 v29, v30, v30
	v_fmac_f32_e32 v23, v22, v22
	v_add_f32_e32 v20, v27, v21
	v_add_f32_e32 v21, v29, v23
	v_add_f32_e32 v27, v20, v21
	global_store_dwordx4 v[24:25], v[10:13], off
	v_lshlrev_b32_e32 v20, 16, v14
	v_and_b32_e32 v21, 0xffff0000, v14
	v_lshlrev_b32_e32 v14, 16, v15
	v_and_b32_e32 v15, 0xffff0000, v15
	v_lshlrev_b32_e32 v22, 16, v16
	v_and_b32_e32 v23, 0xffff0000, v16
	v_lshlrev_b32_e32 v16, 16, v17
	v_and_b32_e32 v17, 0xffff0000, v17
	v_pk_mul_f32 v[20:21], v[26:27], v[20:21] op_sel_hi:[0,1]
	v_pk_mul_f32 v[14:15], v[26:27], v[14:15] op_sel_hi:[0,1]
	v_pk_mul_f32 v[22:23], v[26:27], v[22:23] op_sel_hi:[0,1]
	v_pk_mul_f32 v[16:17], v[26:27], v[16:17] op_sel_hi:[0,1]
	v_pk_fma_f32 v[8:9], v[128:129], v[14:15], v[8:9]
	v_pk_fma_f32 v[6:7], v[124:125], v[20:21], v[6:7]
	v_pk_fma_f32 v[14:15], v[126:127], v[16:17], v[4:5]
	v_pk_fma_f32 v[16:17], v[122:123], v[22:23], v[2:3]
	v_mul_f32_e32 v2, v7, v7
	v_mul_f32_e32 v3, v9, v9
	v_mul_f32_e32 v4, v17, v17
	v_mul_f32_e32 v5, v15, v15
	v_fmac_f32_e32 v2, v6, v6
	v_fmac_f32_e32 v3, v8, v8
	v_fmac_f32_e32 v4, v16, v16
	v_fmac_f32_e32 v5, v14, v14
	v_add_f32_e32 v2, v2, v3
	v_add_f32_e32 v3, v4, v5
	v_add_f32_e32 v2, v2, v3
	v_add_f32_e32 v2, v27, v2
	ds_bpermute_b32 v3, v172, v2
	v_cvt_pk_bf16_f32 v4, v6, v7
	v_cvt_pk_bf16_f32 v5, v8, v9
	v_cvt_pk_bf16_f32 v6, v16, v17
	v_cvt_pk_bf16_f32 v7, v14, v15
	s_waitcnt lgkmcnt(0)
	v_add_f32_e32 v2, v2, v3
	ds_bpermute_b32 v3, v116, v2
	global_store_dwordx4 v[24:25], v[4:7], off offset:256
	s_and_saveexec_b64 s[30:31], s[6:7]
	s_cbranch_execz .LBB0_1249
	v_lshlrev_b64 v[4:5], 6, v[18:19]
	v_lshl_add_u64 v[4:5], s[8:9], 0, v[4:5]
	v_lshl_add_u64 v[4:5], s[28:29], 2, v[4:5]
	s_lshl_b32 s16, s53, 2
	v_lshl_add_u64 v[4:5], v[4:5], 0, s[16:17]
	s_waitcnt lgkmcnt(0)
	v_add_f32_e32 v2, v2, v3
	global_store_dword v[4:5], v2, off
